# combo: counted K/V staging waits + max3-only row-max tree in diff-attention unmasked loops (no canonicalize copies) + 12-deep K fragment reads in MLA unmasked loop + no barrier after weight prep
# speedup vs baseline: 1.0148x; 1.0050x over previous
.LBB0_194:
	v_add_u32_e32 v3, s4, v134
	ds_read_b128 v[38:41], v3 offset:6656
	ds_read_b128 v[42:45], v3
	ds_read_b128 v[120:123], v3 offset:32
	ds_read_b128 v[124:127], v3 offset:6688
	ds_read_b128 v[204:207], v3 offset:64
	ds_read_b128 v[208:211], v3 offset:6720
	ds_read_b128 v[212:215], v3 offset:96
	ds_read_b128 v[216:219], v3 offset:6752
	ds_read_b128 v[220:223], v3 offset:128
	ds_read_b128 v[224:227], v3 offset:6784
	ds_read_b128 v[228:231], v3 offset:160
	ds_read_b128 v[232:235], v3 offset:6816
	s_cmp_eq_u32 s7, s23
	s_cselect_b64 s[18:19], -1, 0
	s_waitcnt lgkmcnt(10)
	v_mfma_f32_32x32x16_bf16 v[54:69], v[42:45], v[70:73], 0
	v_cndmask_b32_e64 v4, -v137, v195, s[18:19]
	s_and_b64 vcc, exec, s[18:19]
	s_mov_b64 s[20:21], s[18:19]
	v_mfma_f32_32x32x16_bf16 v[38:53], v[38:41], v[70:73], 0
	s_waitcnt lgkmcnt(9)
	v_mfma_f32_32x32x16_bf16 v[54:69], v[120:123], v[74:77], v[54:69]
	s_waitcnt lgkmcnt(8)
	v_mfma_f32_32x32x16_bf16 v[38:53], v[124:127], v[74:77], v[38:53]
	s_waitcnt lgkmcnt(7)
	v_mfma_f32_32x32x16_bf16 v[54:69], v[204:207], v[78:81], v[54:69]
	s_waitcnt lgkmcnt(6)
	v_mfma_f32_32x32x16_bf16 v[38:53], v[208:211], v[78:81], v[38:53]
	s_waitcnt lgkmcnt(5)
	v_mfma_f32_32x32x16_bf16 v[54:69], v[212:215], v[82:85], v[54:69]
	s_waitcnt lgkmcnt(4)
	v_mfma_f32_32x32x16_bf16 v[38:53], v[216:219], v[82:85], v[38:53]
	s_waitcnt lgkmcnt(3)
	v_mfma_f32_32x32x16_bf16 v[54:69], v[220:223], v[86:89], v[54:69]
	s_waitcnt lgkmcnt(2)
	v_mfma_f32_32x32x16_bf16 v[38:53], v[224:227], v[86:89], v[38:53]
	s_waitcnt lgkmcnt(1)
	v_mfma_f32_32x32x16_bf16 v[54:69], v[228:231], v[90:93], v[54:69]
	s_waitcnt lgkmcnt(0)
	v_mfma_f32_32x32x16_bf16 v[38:53], v[232:235], v[90:93], v[38:53]
	s_nop 9
	v_fma_f32 v128, v54, s88, v4
	v_fma_f32 v129, v55, s88, v4
	v_fma_f32 v124, v56, s88, v4
	v_fma_f32 v125, v57, s88, v4
	v_fma_f32 v120, v58, s88, v4
	v_fma_f32 v121, v59, s88, v4
	v_pk_fma_f32 v[58:59], v[60:61], s[88:89], v[4:5] op_sel_hi:[1,0,0]
	v_pk_fma_f32 v[54:55], v[62:63], s[88:89], v[4:5] op_sel_hi:[1,0,0]
	v_pk_fma_f32 v[130:131], v[38:39], s[88:89], v[4:5] op_sel_hi:[1,0,0]
	v_pk_fma_f32 v[126:127], v[40:41], s[88:89], v[4:5] op_sel_hi:[1,0,0]
	v_max_f32_e32 v3, v129, v131
	v_pk_fma_f32 v[122:123], v[42:43], s[88:89], v[4:5] op_sel_hi:[1,0,0]
	v_pk_fma_f32 v[60:61], v[44:45], s[88:89], v[4:5] op_sel_hi:[1,0,0]
	v_pk_fma_f32 v[56:57], v[46:47], s[88:89], v[4:5] op_sel_hi:[1,0,0]
	v_pk_fma_f32 v[46:47], v[64:65], s[88:89], v[4:5] op_sel_hi:[1,0,0]
	v_pk_fma_f32 v[48:49], v[48:49], s[88:89], v[4:5] op_sel_hi:[1,0,0]
	v_pk_fma_f32 v[42:43], v[66:67], s[88:89], v[4:5] op_sel_hi:[1,0,0]
	v_pk_fma_f32 v[44:45], v[50:51], s[88:89], v[4:5] op_sel_hi:[1,0,0]
	v_pk_fma_f32 v[38:39], v[68:69], s[88:89], v[4:5] op_sel_hi:[1,0,0]
	v_pk_fma_f32 v[40:41], v[52:53], s[88:89], v[4:5] op_sel_hi:[1,0,0]
	v_max3_f32 v3, v128, v130, v3
	v_max_f32_e32 v4, v124, v126
	v_max_f32_e32 v50, v125, v127
	v_max3_f32 v3, v3, v4, v50
	v_max_f32_e32 v4, v120, v122
	v_max_f32_e32 v50, v121, v123
	v_max3_f32 v3, v3, v4, v50
	v_max_f32_e32 v4, v58, v60
	v_max_f32_e32 v50, v59, v61
	v_max3_f32 v3, v3, v4, v50
	v_max_f32_e32 v4, v54, v56
	v_max_f32_e32 v50, v55, v57
	v_max3_f32 v3, v3, v4, v50
	v_max_f32_e32 v4, v46, v48
	v_max_f32_e32 v50, v47, v49
	v_max3_f32 v3, v3, v4, v50
	v_max_f32_e32 v4, v42, v44
	v_max_f32_e32 v50, v43, v45
	v_max3_f32 v3, v3, v4, v50
	v_max_f32_e32 v4, v38, v40
	v_max_f32_e32 v50, v39, v41
	v_max3_f32 v3, v3, v4, v50
	ds_bpermute_b32 v4, v174, v3
	s_waitcnt lgkmcnt(0)
	v_max_f32_e32 v4, v4, v4
	v_max_f32_e32 v3, v3, v4
	v_cmp_lt_f32_e64 s[46:47], s38, v3
	s_cbranch_vccnz .LBB0_196
	s_cmp_lg_u64 s[46:47], 0
	s_cselect_b64 s[20:21], -1, 0

.LBB0_208:
	v_add_u32_e32 v3, s22, v134
	ds_read_b128 v[38:41], v3 offset:6656
	ds_read_b128 v[42:45], v3
	ds_read_b128 v[120:123], v3 offset:32
	ds_read_b128 v[124:127], v3 offset:6688
	ds_read_b128 v[204:207], v3 offset:64
	ds_read_b128 v[208:211], v3 offset:6720
	ds_read_b128 v[212:215], v3 offset:96
	ds_read_b128 v[216:219], v3 offset:6752
	ds_read_b128 v[220:223], v3 offset:128
	ds_read_b128 v[224:227], v3 offset:6784
	ds_read_b128 v[228:231], v3 offset:160
	ds_read_b128 v[232:235], v3 offset:6816
	s_cmp_eq_u32 s25, s23
	s_cselect_b64 s[18:19], -1, 0
	s_waitcnt lgkmcnt(10)
	v_mfma_f32_32x32x16_bf16 v[54:69], v[42:45], v[70:73], 0
	v_cndmask_b32_e64 v4, -v137, v195, s[18:19]
	s_and_b64 vcc, exec, s[18:19]
	s_mov_b64 s[20:21], s[18:19]
	v_mfma_f32_32x32x16_bf16 v[38:53], v[38:41], v[70:73], 0
	s_waitcnt lgkmcnt(9)
	v_mfma_f32_32x32x16_bf16 v[54:69], v[120:123], v[74:77], v[54:69]
	s_waitcnt lgkmcnt(8)
	v_mfma_f32_32x32x16_bf16 v[38:53], v[124:127], v[74:77], v[38:53]
	s_waitcnt lgkmcnt(7)
	v_mfma_f32_32x32x16_bf16 v[54:69], v[204:207], v[78:81], v[54:69]
	s_waitcnt lgkmcnt(6)
	v_mfma_f32_32x32x16_bf16 v[38:53], v[208:211], v[78:81], v[38:53]
	s_waitcnt lgkmcnt(5)
	v_mfma_f32_32x32x16_bf16 v[54:69], v[212:215], v[82:85], v[54:69]
	s_waitcnt lgkmcnt(4)
	v_mfma_f32_32x32x16_bf16 v[38:53], v[216:219], v[82:85], v[38:53]
	s_waitcnt lgkmcnt(3)
	v_mfma_f32_32x32x16_bf16 v[54:69], v[220:223], v[86:89], v[54:69]
	s_waitcnt lgkmcnt(2)
	v_mfma_f32_32x32x16_bf16 v[38:53], v[224:227], v[86:89], v[38:53]
	s_waitcnt lgkmcnt(1)
	v_mfma_f32_32x32x16_bf16 v[54:69], v[228:231], v[90:93], v[54:69]
	s_waitcnt lgkmcnt(0)
	v_mfma_f32_32x32x16_bf16 v[38:53], v[232:235], v[90:93], v[38:53]
	s_nop 9
	v_fma_f32 v128, v54, s88, v4
	v_fma_f32 v129, v55, s88, v4
	v_fma_f32 v124, v56, s88, v4
	v_fma_f32 v125, v57, s88, v4
	v_fma_f32 v120, v58, s88, v4
	v_fma_f32 v121, v59, s88, v4
	v_pk_fma_f32 v[58:59], v[60:61], s[88:89], v[4:5] op_sel_hi:[1,0,0]
	v_pk_fma_f32 v[54:55], v[62:63], s[88:89], v[4:5] op_sel_hi:[1,0,0]
	v_pk_fma_f32 v[130:131], v[38:39], s[88:89], v[4:5] op_sel_hi:[1,0,0]
	v_pk_fma_f32 v[126:127], v[40:41], s[88:89], v[4:5] op_sel_hi:[1,0,0]
	v_max_f32_e32 v3, v129, v131
	v_pk_fma_f32 v[122:123], v[42:43], s[88:89], v[4:5] op_sel_hi:[1,0,0]
	v_pk_fma_f32 v[60:61], v[44:45], s[88:89], v[4:5] op_sel_hi:[1,0,0]
	v_pk_fma_f32 v[56:57], v[46:47], s[88:89], v[4:5] op_sel_hi:[1,0,0]
	v_pk_fma_f32 v[46:47], v[64:65], s[88:89], v[4:5] op_sel_hi:[1,0,0]
	v_pk_fma_f32 v[48:49], v[48:49], s[88:89], v[4:5] op_sel_hi:[1,0,0]
	v_pk_fma_f32 v[42:43], v[66:67], s[88:89], v[4:5] op_sel_hi:[1,0,0]
	v_pk_fma_f32 v[44:45], v[50:51], s[88:89], v[4:5] op_sel_hi:[1,0,0]
	v_pk_fma_f32 v[38:39], v[68:69], s[88:89], v[4:5] op_sel_hi:[1,0,0]
	v_pk_fma_f32 v[40:41], v[52:53], s[88:89], v[4:5] op_sel_hi:[1,0,0]
	v_max3_f32 v3, v128, v130, v3
	v_max_f32_e32 v4, v124, v126
	v_max_f32_e32 v50, v125, v127
	v_max3_f32 v3, v3, v4, v50
	v_max_f32_e32 v4, v120, v122
	v_max_f32_e32 v50, v121, v123
	v_max3_f32 v3, v3, v4, v50
	v_max_f32_e32 v4, v58, v60
	v_max_f32_e32 v50, v59, v61
	v_max3_f32 v3, v3, v4, v50
	v_max_f32_e32 v4, v54, v56
	v_max_f32_e32 v50, v55, v57
	v_max3_f32 v3, v3, v4, v50
	v_max_f32_e32 v4, v46, v48
	v_max_f32_e32 v50, v47, v49
	v_max3_f32 v3, v3, v4, v50
	v_max_f32_e32 v4, v42, v44
	v_max_f32_e32 v50, v43, v45
	v_max3_f32 v3, v3, v4, v50
	v_max_f32_e32 v4, v38, v40
	v_max_f32_e32 v50, v39, v41
	v_max3_f32 v3, v3, v4, v50
	ds_bpermute_b32 v4, v174, v3
	s_waitcnt lgkmcnt(0)
	v_max_f32_e32 v4, v4, v4
	v_max_f32_e32 v3, v3, v4
	v_cmp_lt_f32_e64 s[46:47], s38, v3
	s_cbranch_vccnz .LBB0_210
	s_cmp_lg_u64 s[46:47], 0
	s_cselect_b64 s[20:21], -1, 0

.LBB0_690:
	v_cvt_f32_i32_e32 v4, v0
	s_cmp_eq_u32 s60, s52
	s_cselect_b64 s[44:45], -1, 0
	v_cndmask_b32_e64 v10, v169, 0, s[44:45]
	v_add_u32_e32 v14, s4, v166
	v_fma_f32 v4, -v154, v4, -v10
	ds_read_b128 v[10:13], v14
	s_mov_b32 s20, 2.0
	s_mov_b32 s22, 0x41200000
	s_mov_b32 s24, 0x41800000
	s_mov_b32 s28, 0x41900000
	s_mov_b32 s21, 0x40400000
	s_mov_b32 s23, 0x41300000
	s_mov_b32 s25, 0x41880000
	s_mov_b32 s29, 0x41980000
	v_fma_f32 v80, 0, v154, v4
	v_add_f32_e32 v81, v154, v4
	v_pk_fma_f32 v[82:83], v[154:155], s[20:21], v[4:5] op_sel_hi:[1,1,0]
	v_pk_fma_f32 v[84:85], v[154:155], s[38:39], v[4:5] op_sel_hi:[1,1,0]
	v_pk_fma_f32 v[86:87], v[154:155], s[22:23], v[4:5] op_sel_hi:[1,1,0]
	v_pk_fma_f32 v[88:89], v[154:155], s[24:25], v[4:5] op_sel_hi:[1,1,0]
	v_pk_fma_f32 v[90:91], v[154:155], s[28:29], v[4:5] op_sel_hi:[1,1,0]
	v_pk_fma_f32 v[92:93], v[154:155], s[26:27], v[4:5] op_sel_hi:[1,1,0]
	v_pk_fma_f32 v[94:95], v[154:155], s[36:37], v[4:5] op_sel_hi:[1,1,0]
	v_add_f32_e32 v4, v153, v4
	v_fma_f32 v96, 0, v154, v4
	s_waitcnt vmcnt(6) lgkmcnt(0)
	v_mfma_f32_32x32x16_bf16 v[80:95], v[10:13], v[112:115], v[80:95]
	ds_read_b128 v[10:13], v14 offset:32
	v_add_f32_e32 v97, v154, v4
	v_fma_f32 v98, v154, s20, v4
	v_fma_f32 v99, v155, s21, v4
	v_fma_f32 v100, v154, s38, v4
	v_fma_f32 v101, v155, s39, v4
	v_pk_fma_f32 v[102:103], v[154:155], s[22:23], v[4:5] op_sel_hi:[1,1,0]
	v_pk_fma_f32 v[104:105], v[154:155], s[24:25], v[4:5] op_sel_hi:[1,1,0]
	v_pk_fma_f32 v[106:107], v[154:155], s[28:29], v[4:5] op_sel_hi:[1,1,0]
	s_waitcnt vmcnt(5) lgkmcnt(0)
	v_mfma_f32_32x32x16_bf16 v[80:95], v[10:13], v[116:119], v[80:95]
	ds_read_b128 v[10:13], v14 offset:64
	v_fma_f32 v108, v154, s26, v4
	v_fma_f32 v109, v155, s27, v4
	v_fma_f32 v110, v154, s36, v4
	v_fma_f32 v111, v155, s37, v4
	s_cmp_lg_u32 s60, s52
	s_waitcnt vmcnt(4) lgkmcnt(0)
	v_mfma_f32_32x32x16_bf16 v[80:95], v[10:13], v[120:123], v[80:95]
	ds_read_b128 v[10:13], v14 offset:96
	ds_read_b128 v[170:173], v14 offset:4608
	s_waitcnt vmcnt(3) lgkmcnt(1)
	v_mfma_f32_32x32x16_bf16 v[80:95], v[10:13], v[124:127], v[80:95]
	ds_read_b128 v[10:13], v14 offset:4640
	s_waitcnt lgkmcnt(1)
	v_mfma_f32_32x32x16_bf16 v[96:111], v[170:173], v[112:115], v[96:111]
	s_nop 8
	v_max_f32_e32 v4, v81, v81
	s_waitcnt lgkmcnt(0)
	v_mfma_f32_32x32x16_bf16 v[96:111], v[10:13], v[116:119], v[96:111]
	ds_read_b128 v[10:13], v14 offset:4672
	s_waitcnt lgkmcnt(0)
	v_mfma_f32_32x32x16_bf16 v[96:111], v[10:13], v[120:123], v[96:111]
	ds_read_b128 v[10:13], v14 offset:4704
	s_waitcnt lgkmcnt(0)
	v_mfma_f32_32x32x16_bf16 v[96:111], v[10:13], v[124:127], v[96:111]
	s_nop 11
	v_max3_f32 v10, v97, v82, v98
	v_max3_f32 v4, v4, v83, v99
	v_max3_f32 v10, v10, v80, v96
	v_max3_f32 v4, v4, v84, v100
	v_max3_f32 v10, v10, v85, v101
	v_max3_f32 v4, v4, v86, v102
	v_max3_f32 v10, v10, v87, v103
	v_max3_f32 v4, v4, v88, v104
	v_max3_f32 v10, v10, v89, v105
	v_max3_f32 v4, v4, v90, v106
	v_max3_f32 v10, v10, v91, v107
	v_max3_f32 v4, v4, v92, v108
	v_max3_f32 v10, v10, v93, v109
	v_max3_f32 v4, v4, v94, v110
	v_max3_f32 v10, v10, v95, v111
	v_max_f32_e32 v4, v4, v10
	ds_bpermute_b32 v10, v174, v4
	s_waitcnt lgkmcnt(0)
	v_max_f32_e32 v10, v10, v10
	v_max_f32_e32 v4, v4, v10
	v_cmp_lt_f32_e32 vcc, s38, v4
	s_cbranch_scc0 .LBB0_695
	s_cmp_lg_u64 vcc, 0
	s_cselect_b64 s[20:21], -1, 0
	s_cbranch_execz .LBB0_696
	s_branch .LBB0_697

.LBB0_693:
	v_add_u32_e32 v4, 64, v0
	v_cvt_f32_i32_e32 v4, v4
	s_cmp_eq_u32 s5, s52
	s_cselect_b64 s[44:45], -1, 0
	v_cndmask_b32_e64 v7, v169, 0, s[44:45]
	v_fma_f32 v4, -v154, v4, -v7
	v_add_u32_e32 v7, s62, v166
	ds_read_b128 v[8:11], v7
	s_mov_b32 s20, 2.0
	s_mov_b32 s22, 0x41200000
	s_mov_b32 s24, 0x41800000
	s_mov_b32 s28, 0x41900000
	s_mov_b32 s21, 0x40400000
	s_mov_b32 s23, 0x41300000
	s_mov_b32 s25, 0x41880000
	s_mov_b32 s29, 0x41980000
	v_fma_f32 v80, 0, v154, v4
	v_add_f32_e32 v81, v154, v4
	v_pk_fma_f32 v[82:83], v[154:155], s[20:21], v[4:5] op_sel_hi:[1,1,0]
	v_pk_fma_f32 v[84:85], v[154:155], s[38:39], v[4:5] op_sel_hi:[1,1,0]
	v_pk_fma_f32 v[86:87], v[154:155], s[22:23], v[4:5] op_sel_hi:[1,1,0]
	v_pk_fma_f32 v[88:89], v[154:155], s[24:25], v[4:5] op_sel_hi:[1,1,0]
	v_pk_fma_f32 v[90:91], v[154:155], s[28:29], v[4:5] op_sel_hi:[1,1,0]
	v_pk_fma_f32 v[92:93], v[154:155], s[26:27], v[4:5] op_sel_hi:[1,1,0]
	v_pk_fma_f32 v[94:95], v[154:155], s[36:37], v[4:5] op_sel_hi:[1,1,0]
	v_add_f32_e32 v4, v153, v4
	v_fma_f32 v96, 0, v154, v4
	s_waitcnt vmcnt(6) lgkmcnt(0)
	v_mfma_f32_32x32x16_bf16 v[80:95], v[8:11], v[112:115], v[80:95]
	ds_read_b128 v[8:11], v7 offset:32
	v_add_f32_e32 v97, v154, v4
	v_fma_f32 v98, v154, s20, v4
	v_fma_f32 v99, v155, s21, v4
	v_fma_f32 v100, v154, s38, v4
	v_fma_f32 v101, v155, s39, v4
	v_pk_fma_f32 v[102:103], v[154:155], s[22:23], v[4:5] op_sel_hi:[1,1,0]
	v_pk_fma_f32 v[104:105], v[154:155], s[24:25], v[4:5] op_sel_hi:[1,1,0]
	v_pk_fma_f32 v[106:107], v[154:155], s[28:29], v[4:5] op_sel_hi:[1,1,0]
	s_waitcnt vmcnt(5) lgkmcnt(0)
	v_mfma_f32_32x32x16_bf16 v[80:95], v[8:11], v[116:119], v[80:95]
	ds_read_b128 v[8:11], v7 offset:64
	v_fma_f32 v108, v154, s26, v4
	v_fma_f32 v109, v155, s27, v4
	v_fma_f32 v110, v154, s36, v4
	v_fma_f32 v111, v155, s37, v4
	s_cmp_lg_u32 s5, s52
	s_waitcnt vmcnt(4) lgkmcnt(0)
	v_mfma_f32_32x32x16_bf16 v[80:95], v[8:11], v[120:123], v[80:95]
	ds_read_b128 v[8:11], v7 offset:96
	ds_read_b128 v[12:15], v7 offset:4608
	s_waitcnt vmcnt(3) lgkmcnt(1)
	v_mfma_f32_32x32x16_bf16 v[80:95], v[8:11], v[124:127], v[80:95]
	ds_read_b128 v[8:11], v7 offset:4640
	s_waitcnt lgkmcnt(1)
	v_mfma_f32_32x32x16_bf16 v[96:111], v[12:15], v[112:115], v[96:111]
	s_nop 8
	v_max_f32_e32 v4, v81, v81
	s_waitcnt lgkmcnt(0)
	v_mfma_f32_32x32x16_bf16 v[96:111], v[8:11], v[116:119], v[96:111]
	ds_read_b128 v[8:11], v7 offset:4672
	s_waitcnt lgkmcnt(0)
	v_mfma_f32_32x32x16_bf16 v[96:111], v[8:11], v[120:123], v[96:111]
	ds_read_b128 v[8:11], v7 offset:4704
	s_waitcnt lgkmcnt(0)
	v_mfma_f32_32x32x16_bf16 v[96:111], v[8:11], v[124:127], v[96:111]
	s_nop 11
	v_max3_f32 v7, v97, v82, v98
	v_max3_f32 v4, v4, v83, v99
	v_max3_f32 v7, v7, v80, v96
	v_max3_f32 v4, v4, v84, v100
	v_max3_f32 v7, v7, v85, v101
	v_max3_f32 v4, v4, v86, v102
	v_max3_f32 v7, v7, v87, v103
	v_max3_f32 v4, v4, v88, v104
	v_max3_f32 v7, v7, v89, v105
	v_max3_f32 v4, v4, v90, v106
	v_max3_f32 v7, v7, v91, v107
	v_max3_f32 v4, v4, v92, v108
	v_max3_f32 v7, v7, v93, v109
	v_max3_f32 v4, v4, v94, v110
	v_max3_f32 v7, v7, v95, v111
	v_max_f32_e32 v4, v4, v7
	ds_bpermute_b32 v7, v174, v4
	s_waitcnt lgkmcnt(0)
	v_max_f32_e32 v7, v7, v7
	v_max_f32_e32 v4, v4, v7
	v_cmp_lt_f32_e32 vcc, s38, v4
	s_cbranch_scc0 .LBB0_700
	s_cmp_lg_u64 vcc, 0
	s_cselect_b64 s[20:21], -1, 0
	s_cbranch_execz .LBB0_701
	s_branch .LBB0_702

.LBB0_743:
	v_cvt_f32_i32_e32 v4, v0
	s_cmp_eq_u32 s22, s7
	s_cselect_b64 s[44:45], -1, 0
	v_cndmask_b32_e64 v10, v225, 0, s[44:45]
	v_add_u32_e32 v14, s4, v222
	v_fma_f32 v4, -v154, v4, -v10
	ds_read_b128 v[10:13], v14
	s_mov_b32 s18, 2.0
	s_mov_b32 s20, 0x41200000
	s_mov_b32 s24, 0x41800000
	s_mov_b32 s28, 0x41900000
	s_mov_b32 s19, 0x40400000
	s_mov_b32 s21, 0x41300000
	s_mov_b32 s25, 0x41880000
	s_mov_b32 s29, 0x41980000
	v_fma_f32 v80, 0, v154, v4
	v_add_f32_e32 v81, v154, v4
	v_pk_fma_f32 v[82:83], v[154:155], s[18:19], v[4:5] op_sel_hi:[1,1,0]
	v_pk_fma_f32 v[84:85], v[154:155], s[38:39], v[4:5] op_sel_hi:[1,1,0]
	v_pk_fma_f32 v[86:87], v[154:155], s[20:21], v[4:5] op_sel_hi:[1,1,0]
	v_pk_fma_f32 v[88:89], v[154:155], s[24:25], v[4:5] op_sel_hi:[1,1,0]
	v_pk_fma_f32 v[90:91], v[154:155], s[28:29], v[4:5] op_sel_hi:[1,1,0]
	v_pk_fma_f32 v[92:93], v[154:155], s[26:27], v[4:5] op_sel_hi:[1,1,0]
	v_pk_fma_f32 v[94:95], v[154:155], s[36:37], v[4:5] op_sel_hi:[1,1,0]
	v_add_f32_e32 v4, v153, v4
	v_fma_f32 v96, 0, v154, v4
	s_waitcnt lgkmcnt(0)
	v_mfma_f32_32x32x16_bf16 v[80:95], v[10:13], v[112:115], v[80:95]
	ds_read_b128 v[10:13], v14 offset:32
	v_add_f32_e32 v97, v154, v4
	v_fma_f32 v98, v154, s18, v4
	v_fma_f32 v99, v155, s19, v4
	v_fma_f32 v100, v154, s38, v4
	v_fma_f32 v101, v155, s39, v4
	v_pk_fma_f32 v[102:103], v[154:155], s[20:21], v[4:5] op_sel_hi:[1,1,0]
	v_pk_fma_f32 v[104:105], v[154:155], s[24:25], v[4:5] op_sel_hi:[1,1,0]
	v_pk_fma_f32 v[106:107], v[154:155], s[28:29], v[4:5] op_sel_hi:[1,1,0]
	s_waitcnt lgkmcnt(0)
	v_mfma_f32_32x32x16_bf16 v[80:95], v[10:13], v[116:119], v[80:95]
	ds_read_b128 v[10:13], v14 offset:64
	v_fma_f32 v108, v154, s26, v4
	v_fma_f32 v109, v155, s27, v4
	v_fma_f32 v110, v154, s36, v4
	v_fma_f32 v111, v155, s37, v4
	s_cmp_lg_u32 s22, s7
	s_waitcnt lgkmcnt(0)
	v_mfma_f32_32x32x16_bf16 v[80:95], v[10:13], v[120:123], v[80:95]
	ds_read_b128 v[10:13], v14 offset:96
	ds_read_b128 v[226:229], v14 offset:4608
	s_waitcnt lgkmcnt(1)
	v_mfma_f32_32x32x16_bf16 v[80:95], v[10:13], v[124:127], v[80:95]
	ds_read_b128 v[10:13], v14 offset:4640
	s_waitcnt lgkmcnt(1)
	v_mfma_f32_32x32x16_bf16 v[96:111], v[226:229], v[112:115], v[96:111]
	s_nop 8
	v_max_f32_e32 v4, v81, v81
	s_waitcnt lgkmcnt(0)
	v_mfma_f32_32x32x16_bf16 v[96:111], v[10:13], v[116:119], v[96:111]
	ds_read_b128 v[10:13], v14 offset:4672
	s_waitcnt lgkmcnt(0)
	v_mfma_f32_32x32x16_bf16 v[96:111], v[10:13], v[120:123], v[96:111]
	ds_read_b128 v[10:13], v14 offset:4704
	s_waitcnt lgkmcnt(0)
	v_mfma_f32_32x32x16_bf16 v[96:111], v[10:13], v[124:127], v[96:111]
	s_nop 11
	v_max3_f32 v10, v97, v82, v98
	v_max3_f32 v4, v4, v83, v99
	v_max3_f32 v10, v10, v80, v96
	v_max3_f32 v4, v4, v84, v100
	v_max3_f32 v10, v10, v85, v101
	v_max3_f32 v4, v4, v86, v102
	v_max3_f32 v10, v10, v87, v103
	v_max3_f32 v4, v4, v88, v104
	v_max3_f32 v10, v10, v89, v105
	v_max3_f32 v4, v4, v90, v106
	v_max3_f32 v10, v10, v91, v107
	v_max3_f32 v4, v4, v92, v108
	v_max3_f32 v10, v10, v93, v109
	v_max3_f32 v4, v4, v94, v110
	v_max3_f32 v10, v10, v95, v111
	v_max_f32_e32 v4, v4, v10
	ds_bpermute_b32 v10, v174, v4
	s_waitcnt lgkmcnt(0)
	v_max_f32_e32 v10, v10, v10
	v_max_f32_e32 v4, v4, v10
	v_cmp_lt_f32_e32 vcc, s38, v4
	s_cbranch_scc0 .LBB0_748
	s_cmp_lg_u64 vcc, 0
	s_cselect_b64 s[18:19], -1, 0
	s_cbranch_execz .LBB0_749
	s_branch .LBB0_750

.LBB0_746:
	v_add_u32_e32 v4, 64, v0
	v_cvt_f32_i32_e32 v4, v4
	s_cmp_eq_u32 s48, s7
	s_cselect_b64 s[44:45], -1, 0
	v_cndmask_b32_e64 v7, v225, 0, s[44:45]
	v_fma_f32 v4, -v154, v4, -v7
	v_add_u32_e32 v7, s23, v222
	ds_read_b128 v[8:11], v7
	s_mov_b32 s18, 2.0
	s_mov_b32 s20, 0x41200000
	s_mov_b32 s24, 0x41800000
	s_mov_b32 s28, 0x41900000
	s_mov_b32 s19, 0x40400000
	s_mov_b32 s21, 0x41300000
	s_mov_b32 s25, 0x41880000
	s_mov_b32 s29, 0x41980000
	v_fma_f32 v80, 0, v154, v4
	v_add_f32_e32 v81, v154, v4
	v_pk_fma_f32 v[82:83], v[154:155], s[18:19], v[4:5] op_sel_hi:[1,1,0]
	v_pk_fma_f32 v[84:85], v[154:155], s[38:39], v[4:5] op_sel_hi:[1,1,0]
	v_pk_fma_f32 v[86:87], v[154:155], s[20:21], v[4:5] op_sel_hi:[1,1,0]
	v_pk_fma_f32 v[88:89], v[154:155], s[24:25], v[4:5] op_sel_hi:[1,1,0]
	v_pk_fma_f32 v[90:91], v[154:155], s[28:29], v[4:5] op_sel_hi:[1,1,0]
	v_pk_fma_f32 v[92:93], v[154:155], s[26:27], v[4:5] op_sel_hi:[1,1,0]
	v_pk_fma_f32 v[94:95], v[154:155], s[36:37], v[4:5] op_sel_hi:[1,1,0]
	v_add_f32_e32 v4, v153, v4
	v_fma_f32 v96, 0, v154, v4
	s_waitcnt lgkmcnt(0)
	v_mfma_f32_32x32x16_bf16 v[80:95], v[8:11], v[112:115], v[80:95]
	ds_read_b128 v[8:11], v7 offset:32
	v_add_f32_e32 v97, v154, v4
	v_fma_f32 v98, v154, s18, v4
	v_fma_f32 v99, v155, s19, v4
	v_fma_f32 v100, v154, s38, v4
	v_fma_f32 v101, v155, s39, v4
	v_pk_fma_f32 v[102:103], v[154:155], s[20:21], v[4:5] op_sel_hi:[1,1,0]
	v_pk_fma_f32 v[104:105], v[154:155], s[24:25], v[4:5] op_sel_hi:[1,1,0]
	v_pk_fma_f32 v[106:107], v[154:155], s[28:29], v[4:5] op_sel_hi:[1,1,0]
	s_waitcnt lgkmcnt(0)
	v_mfma_f32_32x32x16_bf16 v[80:95], v[8:11], v[116:119], v[80:95]
	ds_read_b128 v[8:11], v7 offset:64
	v_fma_f32 v108, v154, s26, v4
	v_fma_f32 v109, v155, s27, v4
	v_fma_f32 v110, v154, s36, v4
	v_fma_f32 v111, v155, s37, v4
	s_cmp_lg_u32 s48, s7
	s_waitcnt lgkmcnt(0)
	v_mfma_f32_32x32x16_bf16 v[80:95], v[8:11], v[120:123], v[80:95]
	ds_read_b128 v[8:11], v7 offset:96
	ds_read_b128 v[12:15], v7 offset:4608
	s_waitcnt lgkmcnt(1)
	v_mfma_f32_32x32x16_bf16 v[80:95], v[8:11], v[124:127], v[80:95]
	ds_read_b128 v[8:11], v7 offset:4640
	s_waitcnt lgkmcnt(1)
	v_mfma_f32_32x32x16_bf16 v[96:111], v[12:15], v[112:115], v[96:111]
	s_nop 8
	v_max_f32_e32 v4, v81, v81
	s_waitcnt lgkmcnt(0)
	v_mfma_f32_32x32x16_bf16 v[96:111], v[8:11], v[116:119], v[96:111]
	ds_read_b128 v[8:11], v7 offset:4672
	s_waitcnt lgkmcnt(0)
	v_mfma_f32_32x32x16_bf16 v[96:111], v[8:11], v[120:123], v[96:111]
	ds_read_b128 v[8:11], v7 offset:4704
	s_waitcnt lgkmcnt(0)
	v_mfma_f32_32x32x16_bf16 v[96:111], v[8:11], v[124:127], v[96:111]
	s_nop 11
	v_max3_f32 v7, v97, v82, v98
	v_max3_f32 v4, v4, v83, v99
	v_max3_f32 v7, v7, v80, v96
	v_max3_f32 v4, v4, v84, v100
	v_max3_f32 v7, v7, v85, v101
	v_max3_f32 v4, v4, v86, v102
	v_max3_f32 v7, v7, v87, v103
	v_max3_f32 v4, v4, v88, v104
	v_max3_f32 v7, v7, v89, v105
	v_max3_f32 v4, v4, v90, v106
	v_max3_f32 v7, v7, v91, v107
	v_max3_f32 v4, v4, v92, v108
	v_max3_f32 v7, v7, v93, v109
	v_max3_f32 v4, v4, v94, v110
	v_max3_f32 v7, v7, v95, v111
	v_max_f32_e32 v4, v4, v7
	ds_bpermute_b32 v7, v174, v4
	s_waitcnt lgkmcnt(0)
	v_max_f32_e32 v7, v7, v7
	v_max_f32_e32 v4, v4, v7
	v_cmp_lt_f32_e32 vcc, s38, v4
	s_cbranch_scc0 .LBB0_753
	s_cmp_lg_u64 vcc, 0
	s_cselect_b64 s[18:19], -1, 0
	s_cbranch_execz .LBB0_754
	s_branch .LBB0_755
